# index: removed the exact no-op '+0.0f' after the merged cross-half add (27 sites; partial sums accumulate from +0 so -0 cannot occur)
# baseline (speedup 1.0000x reference)
; #define MFMA32(a, b, c) __builtin_amdgcn_mfma_f32_32x32x16_bf16((a), (b), (c), 0, 0, 0)
; DI float xhalf_sum(float v) { const auto r = __builtin_amdgcn_permlane32_swap(__float_as_uint(v), __float_as_uint(v), false, false); return __uint_as_float(r[0]) + __uint_as_float(r[1]); }
; DI void phase_index(const Params& p, unsigned char* lds) {
;     ...
;         auto mma = [&](f32x16& s, unsigned off) {
; #pragma unroll
;             for (int i = 0; i < 16; ++i) s[i] = 0.f;
; #pragma unroll
;             for (int ks = 0; ks < 4; ++ks) { const bf16x8 kf = *(const bf16x8*)(lds + off + ks * 32); s = MFMA32(qf[ks], kf, s); }
;         };
;         auto proc = [&](auto PASSC, auto DIAGC, const f32x16& s, int k0, int kb) {
;             constexpr int PASS = decltype(PASSC)::value; constexpr bool DIAG = decltype(DIAGC)::value != 0;
;             f32x4 tot;
; #pragma unroll
;             for (int q = 0; q < 4; ++q) {
;                 float pr = 0.f;
; #pragma unroll
;                 for (int e = 0; e < 4; ++e) pr += wq[q][e] * fmaxf(s[4 * q + e], 0.f);
;                 tot[q] = xhalf_sum(pr);
;             }
;             const int key = k0 + 32 * kb + r32;
; #pragma unroll
;             for (int qq = 0; qq < 2; ++qq) {
;                 const float t_lo = tot[qq], t_hi = tot[2 + qq];
;                 const float sc = ((lane & 32) ? t_hi : t_lo) + 0.0f;
;                 const unsigned ub = __float_as_uint(sc);
;                 const unsigned uk = ub ^ ((unsigned)((int)ub >> 31) | 0x80000000u);
;                 const bool valid = DIAG ? (key <= tq0 + qq) : true;
;                 if (PASS == 0) {
;                     if (valid) { const unsigned a = (uk >> 21) & 0x7feu; atomicAdd((unsigned*)(lds + hbase0 + qq * 2048 + (a & ~3u)), 1u << ((a & 2u) << 3)); }
.LBB0_2567:
	s_bitcmp1_b32 s28, 0
	s_cselect_b32 s34, 0x9000, 0
	v_add_u32_e32 v106, s34, v154
	ds_read_b128 v[2:5], v106
	ds_read_b128 v[6:9], v106 offset:32
	s_cmp_lg_u32 s0, 0
	s_cselect_b64 s[28:29], -1, 0
	s_and_b64 vcc, exec, s[28:29]
	s_waitcnt lgkmcnt(1)
	v_mfma_f32_32x32x16_bf16 v[18:33], v[42:45], v[2:5], 0
	ds_read_b128 v[2:5], v106 offset:64
	ds_read_b128 v[102:105], v106 offset:96
	s_waitcnt lgkmcnt(2)
	v_mfma_f32_32x32x16_bf16 v[18:33], v[34:37], v[6:9], v[18:33]
	s_waitcnt lgkmcnt(1)
	v_mfma_f32_32x32x16_bf16 v[18:33], v[38:41], v[2:5], v[18:33]
	ds_read_b128 v[2:5], v106 offset:4608
	ds_read_b128 v[108:111], v106 offset:4640
	s_waitcnt lgkmcnt(2)
	v_mfma_f32_32x32x16_bf16 v[18:33], v[46:49], v[102:105], v[18:33]
	s_waitcnt lgkmcnt(1)
	v_mfma_f32_32x32x16_bf16 v[2:17], v[42:45], v[2:5], 0
	s_nop 9
	v_max_f32_e32 v18, 0, v18
	v_max_f32_e32 v103, 0, v21
	v_max_f32_e32 v21, 0, v22
	v_max_f32_e32 v102, 0, v20
	v_max_f32_e32 v22, 0, v23
	v_fma_f32 v20, v50, v18, 0
	v_fma_f32 v18, v54, v21, 0
	s_waitcnt lgkmcnt(0)
	v_mfma_f32_32x32x16_bf16 v[2:17], v[34:37], v[108:111], v[2:17]
	v_max_f32_e32 v23, 0, v24
	v_fmac_f32_e32 v18, v55, v22
	v_max_f32_e32 v24, 0, v25
	v_max_f32_e32 v25, 0, v26
	v_fmac_f32_e32 v18, v56, v23
	v_fma_f32 v21, v58, v25, 0
	v_fmac_f32_e32 v18, v57, v24
	ds_read_b128 v[22:25], v106 offset:4672
	v_max_f32_e32 v19, 0, v19
	v_max_f32_e32 v26, 0, v27
	v_max_f32_e32 v27, 0, v28
	v_fmac_f32_e32 v20, v51, v19
	v_fmac_f32_e32 v21, v59, v26
	v_fmac_f32_e32 v21, v60, v27
	v_max_f32_e32 v19, 0, v29
	v_fmac_f32_e32 v21, v61, v19
	v_max_f32_e32 v19, v30, v30
	v_max_f32_e32 v30, 0, v31
	ds_read_b128 v[26:29], v106 offset:4704
	s_waitcnt lgkmcnt(1)
	v_mfma_f32_32x32x16_bf16 v[2:17], v[38:41], v[22:25], v[2:17]
	v_max_f32_e32 v19, 0, v19
	v_fma_f32 v19, v62, v19, 0
	v_fmac_f32_e32 v19, v63, v30
	v_max_f32_e32 v22, 0, v32
	v_fmac_f32_e32 v19, v64, v22
	s_waitcnt lgkmcnt(0)
	v_mfma_f32_32x32x16_bf16 v[2:17], v[46:49], v[26:29], v[2:17]
	v_fmac_f32_e32 v20, v52, v102
	v_max_f32_e32 v22, 0, v33
	v_fmac_f32_e32 v20, v53, v103
	v_fmac_f32_e32 v19, v65, v22
	s_cbranch_vccz .LBB0_2575
	v_mov_b32_e32 v22, v20
	s_nop 1
	v_mov_b32_e32 v23, v18
	s_nop 1
	v_mov_b32_e32 v24, v21
	s_nop 1
	v_permlane32_swap_b32_e32 v22, v24
	v_add_f32_e32 v22, v22, v24
	v_ashrrev_i32_e32 v24, 31, v22
	v_bitop3_b32 v22, v24, v22, s82 bitop3:0x36
	v_lshrrev_b32_e32 v24, 21, v22
	v_lshrrev_b32_e32 v22, 18, v22
	v_and_b32_e32 v24, 0x7fc, v24
	v_and_b32_e32 v22, 16, v22
	v_add_u32_e32 v24, v123, v24
	v_lshlrev_b32_e64 v22, v22, 1
	ds_add_u32 v24, v22
	v_mov_b32_e32 v25, v19
	s_nop 1
	v_permlane32_swap_b32_e32 v23, v25
	v_add_f32_e32 v22, v23, v25
	s_mov_b64 s[30:31], -1
	s_cbranch_execz .LBB0_2576
	s_and_saveexec_b64 s[50:51], s[30:31]
	s_cbranch_execz .LBB0_2571

; DI float xhalf_sum(float v) { const auto r = __builtin_amdgcn_permlane32_swap(__float_as_uint(v), __float_as_uint(v), false, false); return __uint_as_float(r[0]) + __uint_as_float(r[1]); }
; DI void phase_index(const Params& p, unsigned char* lds) {
;     ...
;             for (int q = 0; q < 4; ++q) {
;                 float pr = 0.f;
; #pragma unroll
;                 for (int e = 0; e < 4; ++e) pr += wq[q][e] * fmaxf(s[4 * q + e], 0.f);
;                 tot[q] = xhalf_sum(pr);
;             }
;             const int key = k0 + 32 * kb + r32;
; #pragma unroll
;             for (int qq = 0; qq < 2; ++qq) {
;                 const float t_lo = tot[qq], t_hi = tot[2 + qq];
;                 const float sc = ((lane & 32) ? t_hi : t_lo) + 0.0f;
;                 const unsigned ub = __float_as_uint(sc);
;                 const unsigned uk = ub ^ ((unsigned)((int)ub >> 31) | 0x80000000u);
;                 const bool valid = DIAG ? (key <= tq0 + qq) : true;
;                 if (PASS == 0) {
;                     if (valid) { const unsigned a = (uk >> 21) & 0x7feu; atomicAdd((unsigned*)(lds + hbase0 + qq * 2048 + (a & ~3u)), 1u << ((a & 2u) << 3)); }
.LBB0_2571:
	s_or_b64 exec, exec, s[50:51]
	v_max_f32_e32 v2, 0, v2
	v_fma_f32 v2, v50, v2, 0
	v_max_f32_e32 v3, 0, v3
	v_fmac_f32_e32 v2, v51, v3
	v_max_f32_e32 v3, 0, v4
	v_fmac_f32_e32 v2, v52, v3
	v_max_f32_e32 v3, 0, v5
	v_fmac_f32_e32 v2, v53, v3
	s_and_b64 vcc, exec, s[28:29]
	v_max_f32_e32 v21, v6, v6
	v_max_f32_e32 v20, v7, v7
	v_max_f32_e32 v19, v8, v8
	v_max_f32_e32 v18, v9, v9
	v_max_f32_e32 v10, v10, v10
	v_max_f32_e32 v9, v11, v11
	v_max_f32_e32 v8, v12, v12
	v_max_f32_e32 v7, v13, v13
	v_max_f32_e32 v6, v14, v14
	v_max_f32_e32 v5, v15, v15
	v_max_f32_e32 v4, v16, v16
	v_max_f32_e32 v3, v17, v17
	s_cbranch_vccz .LBB0_2581
	v_mov_b32_e32 v11, v2
	s_nop 1
	v_max_f32_e32 v12, 0, v21
	v_max_f32_e32 v13, 0, v20
	v_pk_mul_f32 v[12:13], v[54:55], v[12:13]
	s_nop 0
	v_add_f32_e32 v12, 0, v12
	v_add_f32_e32 v14, v13, v12
	v_max_f32_e32 v12, 0, v19
	v_max_f32_e32 v13, 0, v18
	v_pk_mul_f32 v[12:13], v[56:57], v[12:13]
	s_mov_b64 s[28:29], -1
	v_add_f32_e32 v12, v12, v14
	v_add_f32_e32 v12, v13, v12
	v_mov_b32_e32 v13, v12
	s_nop 1
	v_permlane32_swap_b32_e32 v12, v13
	v_add_f32_e32 v14, v12, v13
	v_max_f32_e32 v12, 0, v10
	v_fma_f32 v12, v58, v12, 0
	v_max_f32_e32 v13, 0, v9
	v_fmac_f32_e32 v12, v59, v13
	v_max_f32_e32 v13, 0, v8
	v_fmac_f32_e32 v12, v60, v13
	v_max_f32_e32 v13, 0, v7
	v_fmac_f32_e32 v12, v61, v13
	s_nop 1
	v_permlane32_swap_b32_e32 v11, v12
	v_add_f32_e32 v11, v11, v12
	v_max_f32_e32 v12, 0, v6
	v_max_f32_e32 v13, 0, v5
	v_pk_mul_f32 v[12:13], v[62:63], v[12:13]
	v_ashrrev_i32_e32 v15, 31, v11
	v_add_f32_e32 v12, 0, v12
	v_bitop3_b32 v11, v15, v11, s82 bitop3:0x36
	v_add_f32_e32 v16, v13, v12
	v_max_f32_e32 v12, 0, v4
	v_max_f32_e32 v13, 0, v3
	v_lshrrev_b32_e32 v15, 21, v11
	v_lshrrev_b32_e32 v11, 18, v11
	v_pk_mul_f32 v[12:13], v[64:65], v[12:13]
	v_and_b32_e32 v15, 0x7fc, v15
	v_and_b32_e32 v11, 16, v11
	v_add_f32_e32 v12, v12, v16
	v_add_u32_e32 v15, v123, v15
	v_lshlrev_b32_e64 v11, v11, 1
	v_add_f32_e32 v12, v13, v12
	ds_add_u32 v15, v11
	v_mov_b32_e32 v13, v12
	s_nop 1
	v_permlane32_swap_b32_e32 v12, v13
	v_add_f32_e32 v11, v12, v13
	v_cndmask_b32_e64 v13, v11, v14, s[4:5]
	s_cbranch_execz .LBB0_2582
	s_and_saveexec_b64 s[30:31], s[28:29]
	s_cbranch_execnz .LBB0_2587

; DI float xhalf_sum(float v) { const auto r = __builtin_amdgcn_permlane32_swap(__float_as_uint(v), __float_as_uint(v), false, false); return __uint_as_float(r[0]) + __uint_as_float(r[1]); }
; DI void phase_index(const Params& p, unsigned char* lds) {
;     ...
;             for (int q = 0; q < 4; ++q) {
;                 float pr = 0.f;
; #pragma unroll
;                 for (int e = 0; e < 4; ++e) pr += wq[q][e] * fmaxf(s[4 * q + e], 0.f);
;                 tot[q] = xhalf_sum(pr);
;             }
;             const int key = k0 + 32 * kb + r32;
; #pragma unroll
;             for (int qq = 0; qq < 2; ++qq) {
;                 const float t_lo = tot[qq], t_hi = tot[2 + qq];
;                 const float sc = ((lane & 32) ? t_hi : t_lo) + 0.0f;
;                 const unsigned ub = __float_as_uint(sc);
;                 const unsigned uk = ub ^ ((unsigned)((int)ub >> 31) | 0x80000000u);
;                 const bool valid = DIAG ? (key <= tq0 + qq) : true;
;                 if (PASS == 0) {
;                     if (valid) { const unsigned a = (uk >> 21) & 0x7feu; atomicAdd((unsigned*)(lds + hbase0 + qq * 2048 + (a & ~3u)), 1u << ((a & 2u) << 3)); }
.LBB0_2576:
	v_permlane32_swap_b32_e32 v20, v21
	v_permlane32_swap_b32_e32 v18, v19
	v_cmp_le_i32_e32 vcc, v83, v95
	s_and_saveexec_b64 s[50:51], vcc
	s_cbranch_execz .LBB0_2578
	v_add_f32_e32 v20, v20, v21
	v_ashrrev_i32_e32 v21, 31, v20
	v_bitop3_b32 v20, v21, v20, s82 bitop3:0x36
	v_lshrrev_b32_e32 v21, 21, v20
	v_lshrrev_b32_e32 v20, 18, v20
	v_and_b32_e32 v21, 0x7fc, v21
	v_and_b32_e32 v20, 16, v20
	v_add_u32_e32 v21, v123, v21
	v_lshlrev_b32_e64 v20, v20, 1
	ds_add_u32 v21, v20

; DI float xhalf_sum(float v) { const auto r = __builtin_amdgcn_permlane32_swap(__float_as_uint(v), __float_as_uint(v), false, false); return __uint_as_float(r[0]) + __uint_as_float(r[1]); }
; DI void phase_index(const Params& p, unsigned char* lds) {
;     ...
;             for (int q = 0; q < 4; ++q) {
;                 float pr = 0.f;
; #pragma unroll
;                 for (int e = 0; e < 4; ++e) pr += wq[q][e] * fmaxf(s[4 * q + e], 0.f);
;                 tot[q] = xhalf_sum(pr);
;             }
;             const int key = k0 + 32 * kb + r32;
; #pragma unroll
;             for (int qq = 0; qq < 2; ++qq) {
;                 const float t_lo = tot[qq], t_hi = tot[2 + qq];
;                 const float sc = ((lane & 32) ? t_hi : t_lo) + 0.0f;
;                 const unsigned ub = __float_as_uint(sc);
;                 const unsigned uk = ub ^ ((unsigned)((int)ub >> 31) | 0x80000000u);
;                 const bool valid = DIAG ? (key <= tq0 + qq) : true;
;                 if (PASS == 0) {
;                     if (valid) { const unsigned a = (uk >> 21) & 0x7feu; atomicAdd((unsigned*)(lds + hbase0 + qq * 2048 + (a & ~3u)), 1u << ((a & 2u) << 3)); }
.LBB0_2582:
	v_max_f32_e32 v11, 0, v21
	v_max_f32_e32 v10, 0, v10
	v_max_f32_e32 v6, 0, v6
	v_fma_f32 v11, v54, v11, 0
	v_max_f32_e32 v12, 0, v20
	v_fma_f32 v10, v58, v10, 0
	v_max_f32_e32 v9, 0, v9
	v_fma_f32 v6, v62, v6, 0
	v_max_f32_e32 v5, 0, v5
	v_fmac_f32_e32 v11, v55, v12
	v_max_f32_e32 v12, 0, v19
	v_fmac_f32_e32 v10, v59, v9
	v_max_f32_e32 v8, 0, v8
	v_fmac_f32_e32 v6, v63, v5
	v_max_f32_e32 v4, 0, v4
	v_fmac_f32_e32 v11, v56, v12
	v_max_f32_e32 v12, 0, v18
	v_fmac_f32_e32 v10, v60, v8
	v_max_f32_e32 v7, 0, v7
	v_fmac_f32_e32 v6, v64, v4
	v_max_f32_e32 v3, 0, v3
	v_fmac_f32_e32 v11, v57, v12
	v_fmac_f32_e32 v10, v61, v7
	v_fmac_f32_e32 v6, v65, v3
	v_add_u32_e32 v4, 32, v83
	v_permlane32_swap_b32_e32 v2, v10
	v_permlane32_swap_b32_e32 v11, v6
	v_cmp_le_i32_e32 vcc, v4, v95
	s_and_saveexec_b64 s[30:31], vcc
	s_cbranch_execz .LBB0_2584
	v_add_f32_e32 v2, v2, v10
	v_ashrrev_i32_e32 v4, 31, v2
	v_bitop3_b32 v2, v4, v2, s82 bitop3:0x36
	v_lshrrev_b32_e32 v4, 21, v2
	v_lshrrev_b32_e32 v2, 18, v2
	v_and_b32_e32 v4, 0x7fc, v4
	v_and_b32_e32 v2, 16, v2
	v_add_u32_e32 v4, v123, v4
	v_lshlrev_b32_e64 v2, v2, 1
	ds_add_u32 v4, v2

; DI float xhalf_sum(float v) { const auto r = __builtin_amdgcn_permlane32_swap(__float_as_uint(v), __float_as_uint(v), false, false); return __uint_as_float(r[0]) + __uint_as_float(r[1]); }
; DI void phase_index(const Params& p, unsigned char* lds) {
;     ...
;             for (int q = 0; q < 4; ++q) {
;                 float pr = 0.f;
; #pragma unroll
;                 for (int e = 0; e < 4; ++e) pr += wq[q][e] * fmaxf(s[4 * q + e], 0.f);
;                 tot[q] = xhalf_sum(pr);
;             }
;             const int key = k0 + 32 * kb + r32;
; #pragma unroll
;             for (int qq = 0; qq < 2; ++qq) {
;                 const float t_lo = tot[qq], t_hi = tot[2 + qq];
;                 const float sc = ((lane & 32) ? t_hi : t_lo) + 0.0f;
;                 const unsigned ub = __float_as_uint(sc);
;                 const unsigned uk = ub ^ ((unsigned)((int)ub >> 31) | 0x80000000u);
;                 const bool valid = DIAG ? (key <= tq0 + qq) : true;
;                 if (PASS == 0) {
;                     if (valid) { const unsigned a = (uk >> 21) & 0x7feu; atomicAdd((unsigned*)(lds + hbase0 + qq * 2048 + (a & ~3u)), 1u << ((a & 2u) << 3)); }
;                 } else if (PASS == 1) {
;                     if (valid && (int)(uk >> 22) == b1v[qq]) { const unsigned a = (uk >> 11) & 0x7feu; atomicAdd((unsigned*)(lds + hbase0 + qq * 2048 + (a & ~3u)), 1u << ((a & 2u) << 3)); }
;                 } else if (PASS == 3) {
;                     if (valid) {
;                         const int k10 = (int)(uk >> 22), d = k10 - b1v[qq];
;                         if (k10 > hiv[qq]) cntA[qq] += 1;
;                         else if (d >= 0) {
;                             const unsigned bin = ((unsigned)d << sbv[qq]) | ((uk >> (22 - sbv[qq])) & ((1u << sbv[qq]) - 1u));
;                             const unsigned a = bin << 1;
;                             atomicAdd((unsigned*)(lds + hbase0 + qq * 2048 + (a & ~3u)), 1u << ((a & 2u) << 3));
;                         }
;                     }
.LBB0_2639:
	v_max_f32_e32 v18, 0, v18
	v_fma_f32 v168, v50, v18, 0
	v_max_f32_e32 v18, 0, v19
	v_fmac_f32_e32 v168, v51, v18
	v_max_f32_e32 v18, 0, v20
	v_fmac_f32_e32 v168, v52, v18
	v_max_f32_e32 v18, 0, v21
	v_fmac_f32_e32 v168, v53, v18
	v_max_f32_e32 v18, 0, v22
	v_fma_f32 v18, v54, v18, 0
	v_max_f32_e32 v19, 0, v23
	v_fmac_f32_e32 v18, v55, v19
	v_max_f32_e32 v19, 0, v24
	v_fmac_f32_e32 v18, v56, v19
	v_max_f32_e32 v19, 0, v25
	v_fmac_f32_e32 v18, v57, v19
	v_max_f32_e32 v19, 0, v26
	v_fma_f32 v20, v58, v19, 0
	v_max_f32_e32 v19, 0, v27
	v_fmac_f32_e32 v20, v59, v19
	v_max_f32_e32 v19, 0, v28
	v_fmac_f32_e32 v20, v60, v19
	v_max_f32_e32 v19, 0, v29
	v_fmac_f32_e32 v20, v61, v19
	v_max_f32_e32 v19, 0, v30
	v_fma_f32 v19, v62, v19, 0
	v_max_f32_e32 v21, 0, v31
	v_fmac_f32_e32 v19, v63, v21
	v_max_f32_e32 v21, 0, v32
	v_fmac_f32_e32 v19, v64, v21
	v_max_f32_e32 v21, 0, v33
	v_fmac_f32_e32 v19, v65, v21
	s_mov_b64 s[30:31], -1
	s_and_b64 vcc, exec, s[28:29]
	s_cbranch_vccz .LBB0_2653
	v_mov_b32_e32 v21, v168
	v_mov_b32_e32 v23, v20
	s_nop 0
	s_nop 0
	v_permlane32_swap_b32_e32 v21, v23
	v_add_f32_e32 v25, v21, v23
	v_ashrrev_i32_e32 v26, 31, v25
	v_bitop3_b32 v25, v26, v25, s82 bitop3:0x36
	v_mov_b32_e32 v21, v18
	v_mov_b32_e32 v23, v19
	v_lshrrev_b32_e32 v26, 22, v25
	s_nop 0
	v_permlane32_swap_b32_e32 v21, v23
	v_cmp_le_i32_e32 vcc, v26, v101
	s_and_saveexec_b64 s[28:29], vcc
	s_xor_b64 s[28:29], exec, s[28:29]
	s_cbranch_execz .LBB0_2644
	v_sub_u32_e32 v26, v26, v100
	v_cmp_lt_i32_e32 vcc, -1, v26
	s_and_saveexec_b64 s[30:31], vcc
	s_cbranch_execz .LBB0_2643
	v_lshrrev_b32_e32 v25, v113, v25
	v_and_b32_e32 v25, v25, v114
	v_lshl_or_b32 v25, v26, v111, v25
	v_lshlrev_b32_e32 v26, 1, v25
	v_and_b32_e32 v26, -4, v26
	v_lshlrev_b32_e32 v25, 4, v25
	v_add_u32_e32 v26, v123, v26
	v_lshlrev_b32_e64 v25, v25, 1
	ds_add_u32 v26, v25

; DI void phase_index(const Params& p, unsigned char* lds) {
;     ...
;                 } else if (PASS == 3) {
;                     if (valid) {
;                         const int k10 = (int)(uk >> 22), d = k10 - b1v[qq];
;                         if (k10 > hiv[qq]) cntA[qq] += 1;
;                         else if (d >= 0) {
;                             const unsigned bin = ((unsigned)d << sbv[qq]) | ((uk >> (22 - sbv[qq])) & ((1u << sbv[qq]) - 1u));
;                             const unsigned a = bin << 1;
;                             atomicAdd((unsigned*)(lds + hbase0 + qq * 2048 + (a & ~3u)), 1u << ((a & 2u) << 3));
;                         }
;                     }
.LBB0_2644:
	s_or_saveexec_b64 s[28:29], s[28:29]
	v_mov_b32_e32 v165, v167
	s_xor_b64 exec, exec, s[28:29]
	v_add_u32_e32 v165, 1, v167
	s_or_b64 exec, exec, s[28:29]
	v_add_f32_e32 v21, v21, v23
	v_ashrrev_i32_e32 v22, 31, v21
	v_bitop3_b32 v21, v22, v21, s82 bitop3:0x36
	v_lshrrev_b32_e32 v22, 22, v21
	v_cmp_le_i32_e32 vcc, v22, v103
	s_and_saveexec_b64 s[28:29], vcc
	s_xor_b64 s[28:29], exec, s[28:29]
	s_cbranch_execz .LBB0_2650
	v_sub_u32_e32 v22, v22, v102
	v_cmp_lt_i32_e32 vcc, -1, v22
	s_and_saveexec_b64 s[30:31], vcc
	s_cbranch_execz .LBB0_2649
	v_lshrrev_b32_e32 v21, v115, v21
	v_and_b32_e32 v21, v21, v116
	v_lshl_or_b32 v21, v22, v112, v21
	v_lshlrev_b32_e32 v22, 1, v21
	v_and_b32_e32 v22, -4, v22
	v_lshlrev_b32_e32 v21, 4, v21
	v_add_u32_e32 v22, v123, v22
	v_lshlrev_b32_e64 v21, v21, 1
	ds_add_u32 v22, v21 offset:2048

; DI void phase_index(const Params& p, unsigned char* lds) {
;     ...
;                 } else if (PASS == 3) {
;                     if (valid) {
;                         const int k10 = (int)(uk >> 22), d = k10 - b1v[qq];
;                         if (k10 > hiv[qq]) cntA[qq] += 1;
;                         else if (d >= 0) {
;                             const unsigned bin = ((unsigned)d << sbv[qq]) | ((uk >> (22 - sbv[qq])) & ((1u << sbv[qq]) - 1u));
;                             const unsigned a = bin << 1;
;                             atomicAdd((unsigned*)(lds + hbase0 + qq * 2048 + (a & ~3u)), 1u << ((a & 2u) << 3));
;                         }
;                     }
.LBB0_2653:
	s_and_b64 vcc, exec, s[30:31]
	s_cbranch_vccz .LBB0_2634
	v_add_u32_e32 v25, 32, v164
	v_permlane32_swap_b32_e32 v168, v20
	v_permlane32_swap_b32_e32 v18, v19
	v_cmp_le_i32_e32 vcc, v25, v95
	s_and_saveexec_b64 s[28:29], vcc
	s_cbranch_execz .LBB0_2662
	v_add_f32_e32 v20, v168, v20
	v_ashrrev_i32_e32 v23, 31, v20
	v_bitop3_b32 v20, v23, v20, s82 bitop3:0x36
	v_lshrrev_b32_e32 v23, 22, v20
	v_cmp_le_i32_e32 vcc, v23, v101
	s_and_saveexec_b64 s[30:31], vcc
	s_xor_b64 s[30:31], exec, s[30:31]
	s_cbranch_execz .LBB0_2659
	v_sub_u32_e32 v23, v23, v100
	v_cmp_lt_i32_e32 vcc, -1, v23
	s_and_saveexec_b64 s[38:39], vcc
	s_cbranch_execz .LBB0_2658
	v_lshrrev_b32_e32 v20, v113, v20
	v_and_b32_e32 v20, v20, v114
	v_lshl_or_b32 v20, v23, v111, v20
	v_lshlrev_b32_e32 v23, 1, v20
	v_and_b32_e32 v23, -4, v23
	v_lshlrev_b32_e32 v20, 4, v20
	v_add_u32_e32 v23, v123, v23
	v_lshlrev_b32_e64 v20, v20, 1
	ds_add_u32 v23, v20

; DI void phase_index(const Params& p, unsigned char* lds) {
;     ...
;                 } else if (PASS == 3) {
;                     if (valid) {
;                         const int k10 = (int)(uk >> 22), d = k10 - b1v[qq];
;                         if (k10 > hiv[qq]) cntA[qq] += 1;
;                         else if (d >= 0) {
;                             const unsigned bin = ((unsigned)d << sbv[qq]) | ((uk >> (22 - sbv[qq])) & ((1u << sbv[qq]) - 1u));
;                             const unsigned a = bin << 1;
;                             atomicAdd((unsigned*)(lds + hbase0 + qq * 2048 + (a & ~3u)), 1u << ((a & 2u) << 3));
;                         }
;                     }
.LBB0_2662:
	s_or_b64 exec, exec, s[28:29]
	v_add_u32_e32 v20, 31, v164
	v_cmp_le_i32_e32 vcc, v20, v95
	s_and_saveexec_b64 s[28:29], vcc
	s_cbranch_execz .LBB0_2633
	v_add_f32_e32 v18, v18, v19
	v_ashrrev_i32_e32 v19, 31, v18
	v_bitop3_b32 v18, v19, v18, s82 bitop3:0x36
	v_lshrrev_b32_e32 v19, 22, v18
	v_cmp_le_i32_e32 vcc, v19, v103
	s_and_saveexec_b64 s[30:31], vcc
	s_xor_b64 s[30:31], exec, s[30:31]
	s_cbranch_execz .LBB0_2667
	v_sub_u32_e32 v19, v19, v102
	v_cmp_lt_i32_e32 vcc, -1, v19
	s_and_saveexec_b64 s[38:39], vcc
	s_cbranch_execz .LBB0_2666
	v_lshrrev_b32_e32 v18, v115, v18
	v_and_b32_e32 v18, v18, v116
	v_lshl_or_b32 v18, v19, v112, v18
	v_lshlrev_b32_e32 v19, 1, v18
	v_and_b32_e32 v19, -4, v19
	v_lshlrev_b32_e32 v18, 4, v18
	v_add_u32_e32 v19, v123, v19
	v_lshlrev_b32_e64 v18, v18, 1
	ds_add_u32 v19, v18 offset:2048

; DI void phase_index(const Params& p, unsigned char* lds) {
;     ...
;                 } else if (PASS == 3) {
;                     if (valid) {
;                         const int k10 = (int)(uk >> 22), d = k10 - b1v[qq];
;                         if (k10 > hiv[qq]) cntA[qq] += 1;
;                         else if (d >= 0) {
;                             const unsigned bin = ((unsigned)d << sbv[qq]) | ((uk >> (22 - sbv[qq])) & ((1u << sbv[qq]) - 1u));
;                             const unsigned a = bin << 1;
;                             atomicAdd((unsigned*)(lds + hbase0 + qq * 2048 + (a & ~3u)), 1u << ((a & 2u) << 3));
;                         }
;                     }
.LBB0_2669:
	s_nop 0
	v_permlane32_swap_b32_e32 v173, v174
	v_add_f32_e32 v167, v173, v174
	v_ashrrev_i32_e32 v178, 31, v167
	v_bitop3_b32 v167, v178, v167, s82 bitop3:0x36
	v_lshrrev_b32_e32 v178, 22, v167
	v_permlane32_swap_b32_e32 v170, v172
	v_cmp_le_i32_e32 vcc, v178, v101
	s_and_saveexec_b64 s[30:31], vcc
	s_xor_b64 s[30:31], exec, s[30:31]
	s_cbranch_execz .LBB0_2673
	v_sub_u32_e32 v178, v178, v100
	v_cmp_lt_i32_e32 vcc, -1, v178
	s_and_saveexec_b64 s[38:39], vcc
	s_cbranch_execz .LBB0_2672
	v_lshrrev_b32_e32 v167, v113, v167
	v_and_b32_e32 v167, v167, v114
	v_lshl_or_b32 v167, v178, v111, v167
	v_lshlrev_b32_e32 v178, 1, v167
	v_and_b32_e32 v178, -4, v178
	v_lshlrev_b32_e32 v167, 4, v167
	v_add_u32_e32 v178, v123, v178
	v_lshlrev_b32_e64 v167, v167, 1
	ds_add_u32 v178, v167

; DI void phase_index(const Params& p, unsigned char* lds) {
;     ...
;                 } else if (PASS == 3) {
;                     if (valid) {
;                         const int k10 = (int)(uk >> 22), d = k10 - b1v[qq];
;                         if (k10 > hiv[qq]) cntA[qq] += 1;
;                         else if (d >= 0) {
;                             const unsigned bin = ((unsigned)d << sbv[qq]) | ((uk >> (22 - sbv[qq])) & ((1u << sbv[qq]) - 1u));
;                             const unsigned a = bin << 1;
;                             atomicAdd((unsigned*)(lds + hbase0 + qq * 2048 + (a & ~3u)), 1u << ((a & 2u) << 3));
;                         }
;                     }
.LBB0_2673:
	s_or_saveexec_b64 s[30:31], s[30:31]
	v_mov_b32_e32 v167, v165
	s_xor_b64 exec, exec, s[30:31]
	v_add_u32_e32 v167, 1, v165
	s_or_b64 exec, exec, s[30:31]
	v_add_f32_e32 v169, v170, v172
	v_ashrrev_i32_e32 v175, 31, v169
	v_bitop3_b32 v169, v175, v169, s82 bitop3:0x36
	v_lshrrev_b32_e32 v175, 22, v169
	v_cmp_le_i32_e32 vcc, v175, v103
	s_and_saveexec_b64 s[30:31], vcc
	s_xor_b64 s[30:31], exec, s[30:31]
	s_cbranch_execz .LBB0_2679
	v_sub_u32_e32 v175, v175, v102
	v_cmp_lt_i32_e32 vcc, -1, v175
	s_and_saveexec_b64 s[38:39], vcc
	s_cbranch_execz .LBB0_2678
	v_lshrrev_b32_e32 v169, v115, v169
	v_and_b32_e32 v169, v169, v116
	v_lshl_or_b32 v169, v175, v112, v169
	v_lshlrev_b32_e32 v175, 1, v169
	v_and_b32_e32 v175, -4, v175
	v_lshlrev_b32_e32 v169, 4, v169
	v_add_u32_e32 v175, v123, v175
	v_lshlrev_b32_e64 v169, v169, 1
	ds_add_u32 v175, v169 offset:2048

; DI void phase_index(const Params& p, unsigned char* lds) {
;     ...
;                 } else if (PASS == 3) {
;                     if (valid) {
;                         const int k10 = (int)(uk >> 22), d = k10 - b1v[qq];
;                         if (k10 > hiv[qq]) cntA[qq] += 1;
;                         else if (d >= 0) {
;                             const unsigned bin = ((unsigned)d << sbv[qq]) | ((uk >> (22 - sbv[qq])) & ((1u << sbv[qq]) - 1u));
;                             const unsigned a = bin << 1;
;                             atomicAdd((unsigned*)(lds + hbase0 + qq * 2048 + (a & ~3u)), 1u << ((a & 2u) << 3));
;                         }
;                     }
.LBB0_2682:
	v_permlane32_swap_b32_e32 v173, v174
	v_permlane32_swap_b32_e32 v170, v172
	v_cmp_le_i32_e32 vcc, v164, v95
	s_and_saveexec_b64 s[30:31], vcc
	s_cbranch_execz .LBB0_2690
	v_add_f32_e32 v173, v173, v174
	v_ashrrev_i32_e32 v174, 31, v173
	v_bitop3_b32 v173, v174, v173, s82 bitop3:0x36
	v_lshrrev_b32_e32 v174, 22, v173
	v_cmp_le_i32_e32 vcc, v174, v101
	s_and_saveexec_b64 s[34:35], vcc
	s_xor_b64 s[38:39], exec, s[34:35]
	s_cbranch_execz .LBB0_2687
	v_sub_u32_e32 v174, v174, v100
	v_cmp_lt_i32_e32 vcc, -1, v174
	s_and_saveexec_b64 s[50:51], vcc
	s_cbranch_execz .LBB0_2686
	v_lshrrev_b32_e32 v173, v113, v173
	v_and_b32_e32 v173, v173, v114
	v_lshl_or_b32 v173, v174, v111, v173
	v_lshlrev_b32_e32 v174, 1, v173
	v_and_b32_e32 v174, -4, v174
	v_lshlrev_b32_e32 v173, 4, v173
	v_add_u32_e32 v174, v123, v174
	v_lshlrev_b32_e64 v173, v173, 1
	ds_add_u32 v174, v173

; DI void phase_index(const Params& p, unsigned char* lds) {
;     ...
;                 } else if (PASS == 3) {
;                     if (valid) {
;                         const int k10 = (int)(uk >> 22), d = k10 - b1v[qq];
;                         if (k10 > hiv[qq]) cntA[qq] += 1;
;                         else if (d >= 0) {
;                             const unsigned bin = ((unsigned)d << sbv[qq]) | ((uk >> (22 - sbv[qq])) & ((1u << sbv[qq]) - 1u));
;                             const unsigned a = bin << 1;
;                             atomicAdd((unsigned*)(lds + hbase0 + qq * 2048 + (a & ~3u)), 1u << ((a & 2u) << 3));
;                         }
;                     }
.LBB0_2690:
	s_or_b64 exec, exec, s[30:31]
	v_cmp_le_i32_e32 vcc, v164, v117
	s_and_saveexec_b64 s[30:31], vcc
	s_cbranch_execz .LBB0_2698
	v_add_f32_e32 v167, v170, v172
	v_ashrrev_i32_e32 v169, 31, v167
	v_bitop3_b32 v167, v169, v167, s82 bitop3:0x36
	v_lshrrev_b32_e32 v169, 22, v167
	v_cmp_le_i32_e32 vcc, v169, v103
	s_and_saveexec_b64 s[34:35], vcc
	s_xor_b64 s[38:39], exec, s[34:35]
	s_cbranch_execz .LBB0_2695
	v_sub_u32_e32 v169, v169, v102
	v_cmp_lt_i32_e32 vcc, -1, v169
	s_and_saveexec_b64 s[50:51], vcc
	s_cbranch_execz .LBB0_2694
	v_lshrrev_b32_e32 v167, v115, v167
	v_and_b32_e32 v167, v167, v116
	v_lshl_or_b32 v167, v169, v112, v167
	v_lshlrev_b32_e32 v169, 1, v167
	v_and_b32_e32 v169, -4, v169
	v_lshlrev_b32_e32 v167, 4, v167
	v_add_u32_e32 v169, v123, v169
	v_lshlrev_b32_e64 v167, v167, 1
	ds_add_u32 v169, v167 offset:2048

; DI float xhalf_sum(float v) { const auto r = __builtin_amdgcn_permlane32_swap(__float_as_uint(v), __float_as_uint(v), false, false); return __uint_as_float(r[0]) + __uint_as_float(r[1]); }
; DI void phase_index(const Params& p, unsigned char* lds) {
;     ...
;             for (int q = 0; q < 4; ++q) {
;                 float pr = 0.f;
; #pragma unroll
;                 for (int e = 0; e < 4; ++e) pr += wq[q][e] * fmaxf(s[4 * q + e], 0.f);
;                 tot[q] = xhalf_sum(pr);
;             }
;             const int key = k0 + 32 * kb + r32;
; #pragma unroll
;             for (int qq = 0; qq < 2; ++qq) {
;                 const float t_lo = tot[qq], t_hi = tot[2 + qq];
;                 const float sc = ((lane & 32) ? t_hi : t_lo) + 0.0f;
;                 const unsigned ub = __float_as_uint(sc);
;                 const unsigned uk = ub ^ ((unsigned)((int)ub >> 31) | 0x80000000u);
;                 const bool valid = DIAG ? (key <= tq0 + qq) : true;
;                 if (PASS == 0) {
;                     if (valid) { const unsigned a = (uk >> 21) & 0x7feu; atomicAdd((unsigned*)(lds + hbase0 + qq * 2048 + (a & ~3u)), 1u << ((a & 2u) << 3)); }
.LBB0_2969:
	v_max_f32_e32 v114, 0, v114
	v_max_f32_e32 v111, 0, v111
	v_max_f32_e32 v106, 0, v106
	v_fma_f32 v114, v54, v114, 0
	v_max_f32_e32 v115, 0, v115
	v_fma_f32 v111, v58, v111, 0
	v_max_f32_e32 v110, 0, v110
	v_fma_f32 v106, v62, v106, 0
	v_max_f32_e32 v105, 0, v105
	v_fmac_f32_e32 v114, v55, v115
	v_max_f32_e32 v113, 0, v113
	v_fmac_f32_e32 v111, v59, v110
	v_max_f32_e32 v109, 0, v109
	v_fmac_f32_e32 v106, v63, v105
	v_max_f32_e32 v104, 0, v104
	v_fmac_f32_e32 v114, v56, v113
	v_max_f32_e32 v112, 0, v112
	v_fmac_f32_e32 v111, v60, v109
	v_max_f32_e32 v108, 0, v108
	v_fmac_f32_e32 v106, v64, v104
	v_max_f32_e32 v103, 0, v103
	v_fmac_f32_e32 v114, v57, v112
	v_fmac_f32_e32 v111, v61, v108
	v_fmac_f32_e32 v106, v65, v103
	s_nop 0
	v_permlane32_swap_b32_e32 v102, v111
	s_nop 0
	v_permlane32_swap_b32_e32 v114, v106
	v_cmp_le_i32_e32 vcc, v101, v95
	s_and_saveexec_b64 s[50:51], vcc
	s_cbranch_execz .LBB0_2971
	v_add_f32_e32 v102, v102, v111
	v_ashrrev_i32_e32 v104, 31, v102
	v_bitop3_b32 v102, v104, v102, s82 bitop3:0x36
	v_lshrrev_b32_e32 v104, 21, v102
	v_lshrrev_b32_e32 v102, 18, v102
	v_and_b32_e32 v104, 0x7fc, v104
	v_and_b32_e32 v102, 16, v102
	v_add_u32_e32 v104, v123, v104
	v_lshlrev_b32_e64 v102, v102, 1
	ds_add_u32 v104, v102

; DI float xhalf_sum(float v) { const auto r = __builtin_amdgcn_permlane32_swap(__float_as_uint(v), __float_as_uint(v), false, false); return __uint_as_float(r[0]) + __uint_as_float(r[1]); }
; DI void phase_index(const Params& p, unsigned char* lds) {
;     ...
;             for (int q = 0; q < 4; ++q) {
;                 float pr = 0.f;
; #pragma unroll
;                 for (int e = 0; e < 4; ++e) pr += wq[q][e] * fmaxf(s[4 * q + e], 0.f);
;                 tot[q] = xhalf_sum(pr);
;             }
;             const int key = k0 + 32 * kb + r32;
; #pragma unroll
;             for (int qq = 0; qq < 2; ++qq) {
;                 const float t_lo = tot[qq], t_hi = tot[2 + qq];
;                 const float sc = ((lane & 32) ? t_hi : t_lo) + 0.0f;
;                 const unsigned ub = __float_as_uint(sc);
;                 const unsigned uk = ub ^ ((unsigned)((int)ub >> 31) | 0x80000000u);
;                 const bool valid = DIAG ? (key <= tq0 + qq) : true;
;                 if (PASS == 0) {
;                     if (valid) { const unsigned a = (uk >> 21) & 0x7feu; atomicAdd((unsigned*)(lds + hbase0 + qq * 2048 + (a & ~3u)), 1u << ((a & 2u) << 3)); }
.LBB0_2977:
	v_max_f32_e32 v18, 0, v18
	v_fma_f32 v18, v50, v18, 0
	v_max_f32_e32 v19, 0, v19
	v_fmac_f32_e32 v18, v51, v19
	v_max_f32_e32 v19, 0, v20
	v_fmac_f32_e32 v18, v52, v19
	v_max_f32_e32 v19, 0, v21
	v_fmac_f32_e32 v18, v53, v19
	s_and_b64 vcc, exec, s[30:31]
	v_max_f32_e32 v105, v22, v22
	v_max_f32_e32 v104, v23, v23
	v_max_f32_e32 v103, v24, v24
	v_max_f32_e32 v102, v25, v25
	v_max_f32_e32 v26, v26, v26
	v_max_f32_e32 v25, v27, v27
	v_max_f32_e32 v24, v28, v28
	v_max_f32_e32 v23, v29, v29
	v_max_f32_e32 v22, v30, v30
	v_max_f32_e32 v21, v31, v31
	v_max_f32_e32 v20, v32, v32
	v_max_f32_e32 v19, v33, v33
	s_cbranch_vccz .LBB0_2980
	v_mov_b32_e32 v27, v18
	s_nop 1
	v_max_f32_e32 v28, 0, v105
	v_max_f32_e32 v29, 0, v104
	v_pk_mul_f32 v[28:29], v[54:55], v[28:29]
	s_nop 0
	v_add_f32_e32 v28, 0, v28
	v_add_f32_e32 v30, v29, v28
	v_max_f32_e32 v28, 0, v103
	v_max_f32_e32 v29, 0, v102
	v_pk_mul_f32 v[28:29], v[56:57], v[28:29]
	s_mov_b64 s[30:31], -1
	v_add_f32_e32 v28, v28, v30
	v_add_f32_e32 v28, v29, v28
	v_mov_b32_e32 v29, v28
	s_nop 1
	v_permlane32_swap_b32_e32 v28, v29
	v_add_f32_e32 v30, v28, v29
	v_max_f32_e32 v28, 0, v26
	v_fma_f32 v28, v58, v28, 0
	v_max_f32_e32 v29, 0, v25
	v_fmac_f32_e32 v28, v59, v29
	v_max_f32_e32 v29, 0, v24
	v_fmac_f32_e32 v28, v60, v29
	v_max_f32_e32 v29, 0, v23
	v_fmac_f32_e32 v28, v61, v29
	s_nop 1
	v_permlane32_swap_b32_e32 v27, v28
	v_add_f32_e32 v27, v27, v28
	v_max_f32_e32 v28, 0, v22
	v_max_f32_e32 v29, 0, v21
	v_pk_mul_f32 v[28:29], v[62:63], v[28:29]
	v_ashrrev_i32_e32 v31, 31, v27
	v_add_f32_e32 v28, 0, v28
	v_bitop3_b32 v27, v31, v27, s82 bitop3:0x36
	v_add_f32_e32 v32, v29, v28
	v_max_f32_e32 v28, 0, v20
	v_max_f32_e32 v29, 0, v19
	v_lshrrev_b32_e32 v31, 21, v27
	v_lshrrev_b32_e32 v27, 18, v27
	v_pk_mul_f32 v[28:29], v[64:65], v[28:29]
	v_and_b32_e32 v31, 0x7fc, v31
	v_and_b32_e32 v27, 16, v27
	v_add_f32_e32 v28, v28, v32
	v_add_u32_e32 v31, v123, v31
	v_lshlrev_b32_e64 v27, v27, 1
	v_add_f32_e32 v28, v29, v28
	ds_add_u32 v31, v27
	v_mov_b32_e32 v29, v28
	s_nop 1
	v_permlane32_swap_b32_e32 v28, v29
	v_add_f32_e32 v27, v28, v29
	v_cndmask_b32_e64 v29, v27, v30, s[4:5]
	s_cbranch_execz .LBB0_2981
	s_branch .LBB0_2986

; DI float xhalf_sum(float v) { const auto r = __builtin_amdgcn_permlane32_swap(__float_as_uint(v), __float_as_uint(v), false, false); return __uint_as_float(r[0]) + __uint_as_float(r[1]); }
; DI void phase_index(const Params& p, unsigned char* lds) {
;     ...
;             for (int q = 0; q < 4; ++q) {
;                 float pr = 0.f;
; #pragma unroll
;                 for (int e = 0; e < 4; ++e) pr += wq[q][e] * fmaxf(s[4 * q + e], 0.f);
;                 tot[q] = xhalf_sum(pr);
;             }
;             const int key = k0 + 32 * kb + r32;
; #pragma unroll
;             for (int qq = 0; qq < 2; ++qq) {
;                 const float t_lo = tot[qq], t_hi = tot[2 + qq];
;                 const float sc = ((lane & 32) ? t_hi : t_lo) + 0.0f;
;                 const unsigned ub = __float_as_uint(sc);
;                 const unsigned uk = ub ^ ((unsigned)((int)ub >> 31) | 0x80000000u);
;                 const bool valid = DIAG ? (key <= tq0 + qq) : true;
;                 if (PASS == 0) {
;                     if (valid) { const unsigned a = (uk >> 21) & 0x7feu; atomicAdd((unsigned*)(lds + hbase0 + qq * 2048 + (a & ~3u)), 1u << ((a & 2u) << 3)); }
.LBB0_2981:
	v_max_f32_e32 v27, 0, v105
	v_max_f32_e32 v26, 0, v26
	v_max_f32_e32 v22, 0, v22
	v_fma_f32 v27, v54, v27, 0
	v_max_f32_e32 v28, 0, v104
	v_fma_f32 v26, v58, v26, 0
	v_max_f32_e32 v25, 0, v25
	v_fma_f32 v22, v62, v22, 0
	v_max_f32_e32 v21, 0, v21
	v_fmac_f32_e32 v27, v55, v28
	v_max_f32_e32 v28, 0, v103
	v_fmac_f32_e32 v26, v59, v25
	v_max_f32_e32 v24, 0, v24
	v_fmac_f32_e32 v22, v63, v21
	v_max_f32_e32 v20, 0, v20
	v_fmac_f32_e32 v27, v56, v28
	v_max_f32_e32 v28, 0, v102
	v_fmac_f32_e32 v26, v60, v24
	v_max_f32_e32 v23, 0, v23
	v_fmac_f32_e32 v22, v64, v20
	v_max_f32_e32 v19, 0, v19
	v_fmac_f32_e32 v27, v57, v28
	v_fmac_f32_e32 v26, v61, v23
	v_fmac_f32_e32 v22, v65, v19
	v_add_u32_e32 v20, 32, v101
	v_permlane32_swap_b32_e32 v18, v26
	v_permlane32_swap_b32_e32 v27, v22
	v_cmp_le_i32_e32 vcc, v20, v95
	s_and_saveexec_b64 s[38:39], vcc
	s_cbranch_execz .LBB0_2983
	v_add_f32_e32 v18, v18, v26
	v_ashrrev_i32_e32 v20, 31, v18
	v_bitop3_b32 v18, v20, v18, s82 bitop3:0x36
	v_lshrrev_b32_e32 v20, 21, v18
	v_lshrrev_b32_e32 v18, 18, v18
	v_and_b32_e32 v20, 0x7fc, v20
	v_and_b32_e32 v18, 16, v18
	v_add_u32_e32 v20, v123, v20
	v_lshlrev_b32_e64 v18, v18, 1
	ds_add_u32 v20, v18

; #define MFMA32(a, b, c) __builtin_amdgcn_mfma_f32_32x32x16_bf16((a), (b), (c), 0, 0, 0)
; DI float xhalf_sum(float v) { const auto r = __builtin_amdgcn_permlane32_swap(__float_as_uint(v), __float_as_uint(v), false, false); return __uint_as_float(r[0]) + __uint_as_float(r[1]); }
; DI void phase_index(const Params& p, unsigned char* lds) {
;     ...
;         auto mma = [&](f32x16& s, unsigned off) {
; #pragma unroll
;             for (int i = 0; i < 16; ++i) s[i] = 0.f;
; #pragma unroll
;             for (int ks = 0; ks < 4; ++ks) { const bf16x8 kf = *(const bf16x8*)(lds + off + ks * 32); s = MFMA32(qf[ks], kf, s); }
;         };
;         auto proc = [&](auto PASSC, auto DIAGC, const f32x16& s, int k0, int kb) {
;             constexpr int PASS = decltype(PASSC)::value; constexpr bool DIAG = decltype(DIAGC)::value != 0;
;             f32x4 tot;
; #pragma unroll
;             for (int q = 0; q < 4; ++q) {
;                 float pr = 0.f;
; #pragma unroll
;                 for (int e = 0; e < 4; ++e) pr += wq[q][e] * fmaxf(s[4 * q + e], 0.f);
;                 tot[q] = xhalf_sum(pr);
;             }
;             const int key = k0 + 32 * kb + r32;
; #pragma unroll
;             for (int qq = 0; qq < 2; ++qq) {
;                 const float t_lo = tot[qq], t_hi = tot[2 + qq];
;                 const float sc = ((lane & 32) ? t_hi : t_lo) + 0.0f;
;                 const unsigned ub = __float_as_uint(sc);
;                 const unsigned uk = ub ^ ((unsigned)((int)ub >> 31) | 0x80000000u);
;                 const bool valid = DIAG ? (key <= tq0 + qq) : true;
;                 if (PASS == 0) {
;                     if (valid) { const unsigned a = (uk >> 21) & 0x7feu; atomicAdd((unsigned*)(lds + hbase0 + qq * 2048 + (a & ~3u)), 1u << ((a & 2u) << 3)); }
;                 } else if (PASS == 1) {
;                     if (valid && (int)(uk >> 22) == b1v[qq]) { const unsigned a = (uk >> 11) & 0x7feu; atomicAdd((unsigned*)(lds + hbase0 + qq * 2048 + (a & ~3u)), 1u << ((a & 2u) << 3)); }
.LBB0_3242:
	v_add_u32_e32 v115, s50, v113
	v_add_u32_e32 v18, 0x11200, v115
	ds_read_b128 v[18:21], v18
	v_add_u32_e32 v22, 0x11220, v115
	ds_read_b128 v[162:165], v22
	v_add_u32_e32 v167, 0x11240, v115
	s_waitcnt lgkmcnt(1)
	v_mfma_f32_32x32x16_bf16 v[18:33], v[42:45], v[18:21], 0
	v_max_f32_e32 v116, 0, v2
	v_max_f32_e32 v170, v6, v6
	v_max_f32_e32 v173, 0, v3
	v_fma_f32 v117, v50, v116, 0
	v_max_f32_e32 v172, v7, v7
	s_waitcnt lgkmcnt(0)
	v_mfma_f32_32x32x16_bf16 v[18:33], v[34:37], v[162:165], v[18:33]
	ds_read_b128 v[162:165], v167
	v_max_f32_e32 v161, 0, v4
	v_fmac_f32_e32 v117, v51, v173
	v_fmac_f32_e32 v117, v52, v161
	v_max_f32_e32 v161, 0, v8
	s_waitcnt lgkmcnt(0)
	v_mfma_f32_32x32x16_bf16 v[18:33], v[38:41], v[162:165], v[18:33]
	v_max_f32_e32 v162, 0, v170
	v_max_f32_e32 v163, 0, v172
	v_fma_f32 v116, v54, v162, 0
	v_fmac_f32_e32 v116, v55, v163
	v_fmac_f32_e32 v116, v56, v161
	v_max_f32_e32 v161, 0, v9
	v_fmac_f32_e32 v116, v57, v161
	v_max_f32_e32 v161, 0, v10
	v_add_u32_e32 v168, 0x11260, v115
	v_fma_f32 v162, v58, v161, 0
	v_max_f32_e32 v174, 0, v5
	ds_read_b128 v[166:169], v168
	v_max_f32_e32 v161, 0, v11
	v_fmac_f32_e32 v162, v59, v161
	v_max_f32_e32 v161, 0, v12
	v_fmac_f32_e32 v162, v60, v161
	v_max_f32_e32 v161, 0, v13
	s_waitcnt lgkmcnt(0)
	v_mfma_f32_32x32x16_bf16 v[18:33], v[46:49], v[166:169], v[18:33]
	v_fmac_f32_e32 v162, v61, v161
	v_max_f32_e32 v161, 0, v14
	v_fma_f32 v161, v62, v161, 0
	v_max_f32_e32 v163, 0, v15
	v_fmac_f32_e32 v161, v63, v163
	v_max_f32_e32 v163, 0, v16
	s_cmp_lg_u32 s0, s51
	v_fmac_f32_e32 v161, v64, v163
	s_cselect_b64 s[30:31], -1, 0
	v_max_f32_e32 v163, 0, v17
	v_fmac_f32_e32 v117, v53, v174
	v_fmac_f32_e32 v161, v65, v163
	s_and_b64 vcc, exec, s[30:31]
	s_cbranch_vccz .LBB0_3246
	s_nop 0
	v_permlane32_swap_b32_e32 v117, v162
	v_add_f32_e32 v167, v117, v162
	v_ashrrev_i32_e32 v168, 31, v167
	v_bitop3_b32 v167, v168, v167, s82 bitop3:0x36
	v_lshrrev_b32_e32 v168, 22, v167
	v_permlane32_swap_b32_e32 v116, v161
	v_cmp_eq_u32_e32 vcc, v168, v108
	s_and_saveexec_b64 s[26:27], vcc
	s_cbranch_execz .LBB0_3245
	v_lshrrev_b32_e32 v168, 11, v167
	v_lshrrev_b32_e32 v167, 8, v167
	v_and_b32_e32 v168, 0x7fc, v168
	v_and_b32_e32 v167, 16, v167
	v_add_u32_e32 v168, v123, v168
	v_lshlrev_b32_e64 v167, v167, 1
	ds_add_u32 v168, v167
.LBB0_3245:
	s_or_b64 exec, exec, s[26:27]
	v_add_f32_e32 v163, v116, v161
	v_ashrrev_i32_e32 v164, 31, v163
	v_bitop3_b32 v163, v164, v163, s82 bitop3:0x36
	v_lshrrev_b32_e32 v164, 22, v163
	v_cmp_eq_u32_e64 s[26:27], v164, v109
	s_branch .LBB0_3251
.LBB0_3246:
	s_mov_b64 s[26:27], 0
	s_cbranch_execz .LBB0_3251
	v_permlane32_swap_b32_e32 v117, v162
	v_permlane32_swap_b32_e32 v116, v161
	v_cmp_le_i32_e32 vcc, v114, v95
	s_and_saveexec_b64 s[26:27], vcc
	s_cbranch_execz .LBB0_3250
	v_add_f32_e32 v117, v117, v162
	v_ashrrev_i32_e32 v162, 31, v117
	v_bitop3_b32 v117, v162, v117, s82 bitop3:0x36
	v_lshrrev_b32_e32 v162, 22, v117
	v_cmp_eq_u32_e32 vcc, v162, v108
	s_and_b64 exec, exec, vcc
	s_cbranch_execz .LBB0_3250
	v_lshrrev_b32_e32 v162, 11, v117
	v_lshrrev_b32_e32 v117, 8, v117
	v_and_b32_e32 v162, 0x7fc, v162
	v_and_b32_e32 v117, 16, v117
	v_add_u32_e32 v162, v123, v162
	v_lshlrev_b32_e64 v117, v117, 1
	ds_add_u32 v162, v117
.LBB0_3250:
	s_or_b64 exec, exec, s[26:27]
	v_add_f32_e32 v116, v116, v161
	v_ashrrev_i32_e32 v117, 31, v116
	v_bitop3_b32 v163, v117, v116, s82 bitop3:0x36
	v_lshrrev_b32_e32 v116, 22, v163
	v_cmp_le_i32_e32 vcc, v114, v110
	v_cmp_eq_u32_e64 s[26:27], v116, v109
	s_and_b64 s[26:27], vcc, s[26:27]

; DI float xhalf_sum(float v) { const auto r = __builtin_amdgcn_permlane32_swap(__float_as_uint(v), __float_as_uint(v), false, false); return __uint_as_float(r[0]) + __uint_as_float(r[1]); }
; DI void phase_index(const Params& p, unsigned char* lds) {
;     ...
;             for (int q = 0; q < 4; ++q) {
;                 float pr = 0.f;
; #pragma unroll
;                 for (int e = 0; e < 4; ++e) pr += wq[q][e] * fmaxf(s[4 * q + e], 0.f);
;                 tot[q] = xhalf_sum(pr);
;             }
;             const int key = k0 + 32 * kb + r32;
; #pragma unroll
;             for (int qq = 0; qq < 2; ++qq) {
;                 const float t_lo = tot[qq], t_hi = tot[2 + qq];
;                 const float sc = ((lane & 32) ? t_hi : t_lo) + 0.0f;
;                 const unsigned ub = __float_as_uint(sc);
;                 const unsigned uk = ub ^ ((unsigned)((int)ub >> 31) | 0x80000000u);
;                 const bool valid = DIAG ? (key <= tq0 + qq) : true;
;                 if (PASS == 0) {
;                     if (valid) { const unsigned a = (uk >> 21) & 0x7feu; atomicAdd((unsigned*)(lds + hbase0 + qq * 2048 + (a & ~3u)), 1u << ((a & 2u) << 3)); }
;                 } else if (PASS == 1) {
;                     if (valid && (int)(uk >> 22) == b1v[qq]) { const unsigned a = (uk >> 11) & 0x7feu; atomicAdd((unsigned*)(lds + hbase0 + qq * 2048 + (a & ~3u)), 1u << ((a & 2u) << 3)); }
.LBB0_3254:
	v_max_f32_e32 v18, 0, v18
	v_fma_f32 v115, v50, v18, 0
	v_max_f32_e32 v18, 0, v19
	v_fmac_f32_e32 v115, v51, v18
	v_max_f32_e32 v18, 0, v20
	v_fmac_f32_e32 v115, v52, v18
	v_max_f32_e32 v18, 0, v21
	v_fmac_f32_e32 v115, v53, v18
	v_max_f32_e32 v18, 0, v22
	v_fma_f32 v18, v54, v18, 0
	v_max_f32_e32 v19, 0, v23
	v_fmac_f32_e32 v18, v55, v19
	v_max_f32_e32 v19, 0, v24
	v_fmac_f32_e32 v18, v56, v19
	v_max_f32_e32 v19, 0, v25
	v_fmac_f32_e32 v18, v57, v19
	v_max_f32_e32 v19, 0, v26
	v_fma_f32 v20, v58, v19, 0
	v_max_f32_e32 v19, 0, v27
	v_fmac_f32_e32 v20, v59, v19
	v_max_f32_e32 v19, 0, v28
	v_fmac_f32_e32 v20, v60, v19
	v_max_f32_e32 v19, 0, v29
	v_fmac_f32_e32 v20, v61, v19
	v_max_f32_e32 v19, 0, v30
	v_fma_f32 v19, v62, v19, 0
	v_max_f32_e32 v21, 0, v31
	v_fmac_f32_e32 v19, v63, v21
	v_max_f32_e32 v21, 0, v32
	v_fmac_f32_e32 v19, v64, v21
	v_max_f32_e32 v21, 0, v33
	v_fmac_f32_e32 v19, v65, v21
	s_and_b64 vcc, exec, s[30:31]
	s_cbranch_vccz .LBB0_3259
	s_nop 0
	v_permlane32_swap_b32_e32 v115, v20
	v_add_f32_e32 v25, v115, v20
	v_ashrrev_i32_e32 v26, 31, v25
	v_bitop3_b32 v25, v26, v25, s82 bitop3:0x36
	v_lshrrev_b32_e32 v26, 22, v25
	v_permlane32_swap_b32_e32 v18, v19
	v_cmp_eq_u32_e32 vcc, v26, v108
	s_and_saveexec_b64 s[26:27], vcc
	s_cbranch_execz .LBB0_3257
	v_lshrrev_b32_e32 v26, 11, v25
	v_lshrrev_b32_e32 v25, 8, v25
	v_and_b32_e32 v26, 0x7fc, v26
	v_and_b32_e32 v25, 16, v25
	v_add_u32_e32 v26, v123, v26
	v_lshlrev_b32_e64 v25, v25, 1
	ds_add_u32 v26, v25
.LBB0_3257:
	s_or_b64 exec, exec, s[26:27]
	v_add_f32_e32 v21, v18, v19
	v_ashrrev_i32_e32 v22, 31, v21
	v_bitop3_b32 v21, v22, v21, s82 bitop3:0x36
	v_lshrrev_b32_e32 v22, 22, v21
	v_cmp_eq_u32_e64 s[26:27], v22, v109
	s_branch .LBB0_3264

; DI float xhalf_sum(float v) { const auto r = __builtin_amdgcn_permlane32_swap(__float_as_uint(v), __float_as_uint(v), false, false); return __uint_as_float(r[0]) + __uint_as_float(r[1]); }
; DI void phase_index(const Params& p, unsigned char* lds) {
;     ...
;             for (int q = 0; q < 4; ++q) {
;                 float pr = 0.f;
; #pragma unroll
;                 for (int e = 0; e < 4; ++e) pr += wq[q][e] * fmaxf(s[4 * q + e], 0.f);
;                 tot[q] = xhalf_sum(pr);
;             }
;             const int key = k0 + 32 * kb + r32;
; #pragma unroll
;             for (int qq = 0; qq < 2; ++qq) {
;                 const float t_lo = tot[qq], t_hi = tot[2 + qq];
;                 const float sc = ((lane & 32) ? t_hi : t_lo) + 0.0f;
;                 const unsigned ub = __float_as_uint(sc);
;                 const unsigned uk = ub ^ ((unsigned)((int)ub >> 31) | 0x80000000u);
;                 const bool valid = DIAG ? (key <= tq0 + qq) : true;
;                 if (PASS == 0) {
;                     if (valid) { const unsigned a = (uk >> 21) & 0x7feu; atomicAdd((unsigned*)(lds + hbase0 + qq * 2048 + (a & ~3u)), 1u << ((a & 2u) << 3)); }
;                 } else if (PASS == 1) {
;                     if (valid && (int)(uk >> 22) == b1v[qq]) { const unsigned a = (uk >> 11) & 0x7feu; atomicAdd((unsigned*)(lds + hbase0 + qq * 2048 + (a & ~3u)), 1u << ((a & 2u) << 3)); }
.LBB0_3259:
	s_mov_b64 s[26:27], 0
	s_cbranch_execz .LBB0_3264
	v_add_u32_e32 v25, 32, v114
	v_permlane32_swap_b32_e32 v115, v20
	v_permlane32_swap_b32_e32 v18, v19
	v_cmp_le_i32_e32 vcc, v25, v95
	s_and_saveexec_b64 s[26:27], vcc
	s_cbranch_execz .LBB0_3263
	v_add_f32_e32 v20, v115, v20
	v_ashrrev_i32_e32 v23, 31, v20
	v_bitop3_b32 v20, v23, v20, s82 bitop3:0x36
	v_lshrrev_b32_e32 v23, 22, v20
	v_cmp_eq_u32_e32 vcc, v23, v108
	s_and_b64 exec, exec, vcc
	s_cbranch_execz .LBB0_3263
	v_lshrrev_b32_e32 v23, 11, v20
	v_lshrrev_b32_e32 v20, 8, v20
	v_and_b32_e32 v23, 0x7fc, v23
	v_and_b32_e32 v20, 16, v20
	v_add_u32_e32 v23, v123, v23
	v_lshlrev_b32_e64 v20, v20, 1
	ds_add_u32 v23, v20
.LBB0_3263:
	s_or_b64 exec, exec, s[26:27]
	v_add_f32_e32 v18, v18, v19
	v_ashrrev_i32_e32 v19, 31, v18
	v_bitop3_b32 v21, v19, v18, s82 bitop3:0x36
	v_add_u32_e32 v18, 31, v114
	v_cmp_le_i32_e32 vcc, v18, v95
	v_lshrrev_b32_e32 v18, 22, v21
	v_cmp_eq_u32_e64 s[26:27], v18, v109
	s_and_b64 s[26:27], vcc, s[26:27]

; DI void phase_index(const Params& p, unsigned char* lds) {
;     ...
;             for (int q = 0; q < 4; ++q) {
;                 float pr = 0.f;
; #pragma unroll
;                 for (int e = 0; e < 4; ++e) pr += wq[q][e] * fmaxf(s[4 * q + e], 0.f);
;                 tot[q] = xhalf_sum(pr);
;             }
;             const int key = k0 + 32 * kb + r32;
; #pragma unroll
;             for (int qq = 0; qq < 2; ++qq) {
;                 const float t_lo = tot[qq], t_hi = tot[2 + qq];
;                 const float sc = ((lane & 32) ? t_hi : t_lo) + 0.0f;
;                 const unsigned ub = __float_as_uint(sc);
;                 const unsigned uk = ub ^ ((unsigned)((int)ub >> 31) | 0x80000000u);
;                 const bool valid = DIAG ? (key <= tq0 + qq) : true;
;                 if (PASS == 0) {
;                     if (valid) { const unsigned a = (uk >> 21) & 0x7feu; atomicAdd((unsigned*)(lds + hbase0 + qq * 2048 + (a & ~3u)), 1u << ((a & 2u) << 3)); }
;                 } else if (PASS == 1) {
;                     if (valid && (int)(uk >> 22) == b1v[qq]) { const unsigned a = (uk >> 11) & 0x7feu; atomicAdd((unsigned*)(lds + hbase0 + qq * 2048 + (a & ~3u)), 1u << ((a & 2u) << 3)); }
;                 } else if (PASS == 3) {
;                     if (valid) {
;                         const int k10 = (int)(uk >> 22), d = k10 - b1v[qq];
;                         if (k10 > hiv[qq]) cntA[qq] += 1;
;                         else if (d >= 0) {
;                             const unsigned bin = ((unsigned)d << sbv[qq]) | ((uk >> (22 - sbv[qq])) & ((1u << sbv[qq]) - 1u));
;                             const unsigned a = bin << 1;
;                             atomicAdd((unsigned*)(lds + hbase0 + qq * 2048 + (a & ~3u)), 1u << ((a & 2u) << 3));
;                         }
;                     }
;                 } else {
;                     const int k20 = (int)(uk >> kshv[qq]);
;                     const u64 bg = __ballot(valid && k20 > tauv[qq]);
;                     const u64 be = __ballot(valid && k20 == tauv[qq]);
;                     Gm[qq] |= (bg & 0xffffffffull) << (32 * kb); Gm[2 + qq] |= (bg >> 32) << (32 * kb);
;                     Em[qq] |= (be & 0xffffffffull) << (32 * kb); Em[2 + qq] |= (be >> 32) << (32 * kb);
;                 }
.LBB0_3524:
	v_max_f32_e32 v18, 0, v18
	v_fma_f32 v18, v50, v18, 0
	v_max_f32_e32 v19, 0, v19
	v_fmac_f32_e32 v18, v51, v19
	v_max_f32_e32 v19, 0, v20
	v_fmac_f32_e32 v18, v52, v19
	v_max_f32_e32 v19, 0, v21
	v_fmac_f32_e32 v18, v53, v19
	v_max_f32_e32 v19, 0, v22
	v_fma_f32 v19, v54, v19, 0
	v_max_f32_e32 v20, 0, v23
	v_fmac_f32_e32 v19, v55, v20
	v_max_f32_e32 v20, 0, v24
	v_fmac_f32_e32 v19, v56, v20
	v_max_f32_e32 v20, 0, v25
	v_fmac_f32_e32 v19, v57, v20
	v_max_f32_e32 v20, 0, v26
	v_fma_f32 v20, v58, v20, 0
	v_max_f32_e32 v21, 0, v27
	v_fmac_f32_e32 v20, v59, v21
	v_max_f32_e32 v21, 0, v28
	v_fmac_f32_e32 v20, v60, v21
	v_max_f32_e32 v21, 0, v29
	v_fmac_f32_e32 v20, v61, v21
	v_max_f32_e32 v21, 0, v30
	v_fma_f32 v21, v62, v21, 0
	v_max_f32_e32 v22, 0, v31
	v_fmac_f32_e32 v21, v63, v22
	v_max_f32_e32 v22, 0, v32
	v_fmac_f32_e32 v21, v64, v22
	v_max_f32_e32 v22, 0, v33
	v_fmac_f32_e32 v21, v65, v22
	s_mov_b64 s[28:29], -1
	s_and_b64 vcc, exec, s[58:59]
	s_cbranch_vccz .LBB0_3526
	v_mov_b32_e32 v22, v18
	v_mov_b32_e32 v23, v19
	v_mov_b32_e32 v26, v20
	v_mov_b32_e32 v27, v21
	s_nop 0
	v_permlane32_swap_b32_e32 v22, v26
	s_nop 0
	v_permlane32_swap_b32_e32 v23, v27
	v_pk_add_f32 v[22:23], v[22:23], v[26:27]
	s_mov_b64 s[28:29], 0
	s_nop 0
	v_ashrrev_i32_e32 v24, 31, v23
	v_ashrrev_i32_e32 v25, 31, v22
	v_or_b32_e32 v24, 0x80000000, v24
	v_or_b32_e32 v25, 0x80000000, v25
	v_xor_b32_e32 v23, v24, v23
	v_xor_b32_e32 v22, v25, v22
	v_lshrrev_b32_e32 v23, v83, v23
	v_lshrrev_b32_e32 v22, v106, v22
	v_cmp_gt_i32_e64 s[58:59], v22, v100
	v_cmp_eq_u32_e64 s[68:69], v22, v100
	v_cmp_gt_i32_e64 s[30:31], v23, v1
	v_cmp_eq_u32_e64 s[26:27], v23, v1
.LBB0_3526:
	s_andn2_b64 vcc, exec, s[28:29]
	s_cbranch_vccnz .LBB0_3528
	v_permlane32_swap_b32_e32 v18, v20
	v_permlane32_swap_b32_e32 v19, v21
	v_pk_add_f32 v[18:19], v[18:19], v[20:21]
	v_or_b32_e32 v26, 32, v164
	v_cmp_le_i32_e32 vcc, v26, v95
	v_ashrrev_i32_e32 v21, 31, v18
	v_ashrrev_i32_e32 v20, 31, v19
	v_or_b32_e32 v21, 0x80000000, v21
	v_or_b32_e32 v20, 0x80000000, v20
	v_xor_b32_e32 v18, v21, v18
	v_xor_b32_e32 v19, v20, v19
	v_lshrrev_b32_e32 v18, v106, v18
	v_add_u32_e32 v26, 31, v164
	v_lshrrev_b32_e32 v19, v83, v19
	v_cmp_gt_i32_e64 s[28:29], v18, v100
	v_cmp_eq_u32_e64 s[30:31], v18, v100
	v_cmp_le_i32_e64 s[26:27], v26, v95
	s_and_b64 s[28:29], vcc, s[28:29]
	s_and_b64 s[30:31], vcc, s[30:31]
	v_cmp_gt_i32_e32 vcc, v19, v1
	s_and_b64 s[58:59], s[28:29], exec
	v_cmp_eq_u32_e64 s[28:29], v19, v1
	s_and_b64 s[68:69], s[30:31], exec
	s_and_b64 s[30:31], s[26:27], vcc
	s_and_b64 s[26:27], s[26:27], s[28:29]
	s_and_b64 s[30:31], s[30:31], exec
	s_and_b64 s[26:27], s[26:27], exec

; DI void phase_index(const Params& p, unsigned char* lds) {
;     ...
;             for (int q = 0; q < 4; ++q) {
;                 float pr = 0.f;
; #pragma unroll
;                 for (int e = 0; e < 4; ++e) pr += wq[q][e] * fmaxf(s[4 * q + e], 0.f);
;                 tot[q] = xhalf_sum(pr);
;             }
;             const int key = k0 + 32 * kb + r32;
; #pragma unroll
;             for (int qq = 0; qq < 2; ++qq) {
;                 const float t_lo = tot[qq], t_hi = tot[2 + qq];
;                 const float sc = ((lane & 32) ? t_hi : t_lo) + 0.0f;
;                 const unsigned ub = __float_as_uint(sc);
;                 const unsigned uk = ub ^ ((unsigned)((int)ub >> 31) | 0x80000000u);
;                 const bool valid = DIAG ? (key <= tq0 + qq) : true;
;                 if (PASS == 0) {
;                     if (valid) { const unsigned a = (uk >> 21) & 0x7feu; atomicAdd((unsigned*)(lds + hbase0 + qq * 2048 + (a & ~3u)), 1u << ((a & 2u) << 3)); }
;                 } else if (PASS == 1) {
;                     if (valid && (int)(uk >> 22) == b1v[qq]) { const unsigned a = (uk >> 11) & 0x7feu; atomicAdd((unsigned*)(lds + hbase0 + qq * 2048 + (a & ~3u)), 1u << ((a & 2u) << 3)); }
;                 } else if (PASS == 3) {
;                     if (valid) {
;                         const int k10 = (int)(uk >> 22), d = k10 - b1v[qq];
;                         if (k10 > hiv[qq]) cntA[qq] += 1;
;                         else if (d >= 0) {
;                             const unsigned bin = ((unsigned)d << sbv[qq]) | ((uk >> (22 - sbv[qq])) & ((1u << sbv[qq]) - 1u));
;                             const unsigned a = bin << 1;
;                             atomicAdd((unsigned*)(lds + hbase0 + qq * 2048 + (a & ~3u)), 1u << ((a & 2u) << 3));
;                         }
;                     }
;                 } else {
;                     const int k20 = (int)(uk >> kshv[qq]);
;                     const u64 bg = __ballot(valid && k20 > tauv[qq]);
;                     const u64 be = __ballot(valid && k20 == tauv[qq]);
;                     Gm[qq] |= (bg & 0xffffffffull) << (32 * kb); Gm[2 + qq] |= (bg >> 32) << (32 * kb);
;                     Em[qq] |= (be & 0xffffffffull) << (32 * kb); Em[2 + qq] |= (be >> 32) << (32 * kb);
;                 }
.LBB0_3555:
	v_mov_b32_e32 v164, v114
	v_mov_b32_e32 v165, v115
	v_mov_b32_e32 v168, v116
	v_mov_b32_e32 v169, v117
	s_nop 0
	v_permlane32_swap_b32_e32 v164, v168
	s_nop 0
	v_permlane32_swap_b32_e32 v165, v169
	v_pk_add_f32 v[164:165], v[164:165], v[168:169]
	s_nop 0
	s_nop 0
	v_ashrrev_i32_e32 v166, 31, v165
	v_ashrrev_i32_e32 v167, 31, v164
	v_or_b32_e32 v166, 0x80000000, v166
	v_or_b32_e32 v167, 0x80000000, v167
	v_xor_b32_e32 v165, v166, v165
	v_xor_b32_e32 v164, v167, v164
	v_lshrrev_b32_e32 v165, v83, v165
	v_lshrrev_b32_e32 v164, v106, v164
	v_cmp_gt_i32_e64 s[52:53], v164, v100
	v_cmp_eq_u32_e64 s[56:57], v164, v100
	v_cmp_gt_i32_e64 s[50:51], v165, v1
	v_cmp_eq_u32_e64 s[54:55], v165, v1
	s_lshl_b32 s28, s36, 6
	v_or_b32_e32 v164, s28, v194
	s_cbranch_execnz .LBB0_3522
.LBB0_3556:
	v_permlane32_swap_b32_e32 v114, v116
	v_permlane32_swap_b32_e32 v115, v117
	v_pk_add_f32 v[114:115], v[114:115], v[116:117]
	v_cmp_le_i32_e32 vcc, v164, v95
	v_cmp_le_i32_e64 s[26:27], v164, v101
	v_ashrrev_i32_e32 v117, 31, v114
	v_ashrrev_i32_e32 v116, 31, v115
	v_or_b32_e32 v117, 0x80000000, v117
	v_or_b32_e32 v116, 0x80000000, v116
	v_xor_b32_e32 v114, v117, v114
	v_xor_b32_e32 v115, v116, v115
	v_lshrrev_b32_e32 v114, v106, v114
	v_lshrrev_b32_e32 v115, v83, v115
	v_cmp_gt_i32_e64 s[28:29], v114, v100
	v_cmp_eq_u32_e64 s[30:31], v114, v100
	s_and_b64 s[28:29], vcc, s[28:29]
	s_and_b64 s[30:31], vcc, s[30:31]
	v_cmp_gt_i32_e32 vcc, v115, v1
	v_cndmask_b32_e64 v116, 0, 1, s[28:29]
	v_cmp_eq_u32_e64 s[28:29], v115, v1
	s_and_b64 s[56:57], s[30:31], exec
	s_and_b64 s[30:31], s[26:27], vcc
	s_and_b64 s[26:27], s[26:27], s[28:29]
	s_and_b64 s[50:51], s[30:31], exec
	v_cndmask_b32_e64 v114, 0, 1, s[26:27]
	v_cmp_ne_u32_e64 s[52:53], 0, v116
	v_cmp_ne_u32_e64 s[54:55], 0, v114
	s_add_i32 s1, s1, 1
	s_cmp_ge_i32 s1, s97
	s_cbranch_scc0 .LBB0_3523
	s_branch .LBB0_3524
